# merge pass loop: all 32 loads of an iteration (with their address arithmetic) issued before the first consumer instead of stalling after 12
# speedup vs baseline: 1.0034x; 1.0034x over previous
.LBB0_495:
	s_nop 0
	v_lshl_add_u64 v[8:9], s[34:35], 0, v[130:131]
	v_add_co_u32_e32 v8, vcc, s11, v8
	s_addk_i32 s10, 0x2000
	s_nop 0
	v_addc_co_u32_e32 v9, vcc, 0, v9, vcc
	global_load_dwordx4 v[84:87], v[8:9], off
	global_load_dwordx4 v[80:83], v[8:9], off offset:256
	v_lshl_add_u64 v[8:9], s[34:35], 0, v[128:129]
	v_add_co_u32_e32 v10, vcc, s12, v8
	v_addc_co_u32_e32 v11, vcc, 0, v9, vcc
	global_load_dword v151, v[10:11], off
	v_add_co_u32_e32 v10, vcc, s13, v8
	v_addc_co_u32_e32 v11, vcc, 0, v9, vcc
	v_add_co_u32_e32 v8, vcc, s16, v8
	global_load_dword v152, v[10:11], off
	v_addc_co_u32_e32 v9, vcc, 0, v9, vcc
	global_load_dword v153, v[8:9], off
	v_lshl_add_u64 v[8:9], s[34:35], 0, v[126:127]
	v_add_co_u32_e32 v10, vcc, s17, v8
	v_addc_co_u32_e32 v11, vcc, 0, v9, vcc
	global_load_dwordx4 v[72:75], v[10:11], off
	v_add_co_u32_e32 v10, vcc, s18, v8
	v_addc_co_u32_e32 v11, vcc, 0, v9, vcc
	v_add_co_u32_e32 v8, vcc, s19, v8
	global_load_dwordx4 v[76:79], v[10:11], off
	v_addc_co_u32_e32 v9, vcc, 0, v9, vcc
	global_load_dwordx4 v[68:71], v[8:9], off
	v_lshl_add_u64 v[8:9], s[34:35], 0, v[116:117]
	v_add_co_u32_e32 v8, vcc, s11, v8
	v_addc_co_u32_e32 v9, vcc, 0, v9, vcc
	global_load_dwordx4 v[64:67], v[8:9], off
	global_load_dwordx4 v[60:63], v[8:9], off offset:256
	v_lshl_add_u64 v[8:9], s[34:35], 0, v[114:115]
	v_add_co_u32_e32 v10, vcc, s12, v8
	v_addc_co_u32_e32 v11, vcc, 0, v9, vcc
	global_load_dword v148, v[10:11], off
	v_add_co_u32_e32 v10, vcc, s13, v8
	v_addc_co_u32_e32 v11, vcc, 0, v9, vcc
	v_add_co_u32_e32 v8, vcc, s16, v8
	global_load_dword v149, v[10:11], off
	v_addc_co_u32_e32 v9, vcc, 0, v9, vcc
	global_load_dword v150, v[8:9], off
	v_lshl_add_u64 v[8:9], s[34:35], 0, v[112:113]
	v_add_co_u32_e32 v10, vcc, s17, v8
	v_addc_co_u32_e32 v11, vcc, 0, v9, vcc
	global_load_dwordx4 v[52:55], v[10:11], off
	v_add_co_u32_e32 v10, vcc, s18, v8
	v_addc_co_u32_e32 v11, vcc, 0, v9, vcc
	v_add_co_u32_e32 v8, vcc, s19, v8
	v_addc_co_u32_e32 v9, vcc, 0, v9, vcc
	global_load_dwordx4 v[56:59], v[10:11], off
	global_load_dwordx4 v[48:51], v[8:9], off
	v_lshl_add_u64 v[8:9], s[34:35], 0, v[106:107]
	v_add_co_u32_e32 v8, vcc, s11, v8
	v_addc_co_u32_e32 v9, vcc, 0, v9, vcc
	global_load_dwordx4 v[44:47], v[8:9], off
	global_load_dwordx4 v[40:43], v[8:9], off offset:256
	v_lshl_add_u64 v[8:9], s[34:35], 0, v[104:105]
	v_add_co_u32_e32 v10, vcc, s12, v8
	v_addc_co_u32_e32 v11, vcc, 0, v9, vcc
	global_load_dword v145, v[10:11], off
	v_add_co_u32_e32 v10, vcc, s13, v8
	v_addc_co_u32_e32 v11, vcc, 0, v9, vcc
	v_add_co_u32_e32 v8, vcc, s16, v8
	v_addc_co_u32_e32 v9, vcc, 0, v9, vcc
	global_load_dword v146, v[10:11], off
	global_load_dword v147, v[8:9], off
	v_lshl_add_u64 v[8:9], s[34:35], 0, v[102:103]
	v_add_co_u32_e32 v10, vcc, s17, v8
	v_addc_co_u32_e32 v11, vcc, 0, v9, vcc
	global_load_dwordx4 v[32:35], v[10:11], off
	v_add_co_u32_e32 v10, vcc, s18, v8
	v_addc_co_u32_e32 v11, vcc, 0, v9, vcc
	v_add_co_u32_e32 v8, vcc, s19, v8
	global_load_dwordx4 v[36:39], v[10:11], off
	v_addc_co_u32_e32 v9, vcc, 0, v9, vcc
	global_load_dwordx4 v[28:31], v[8:9], off
	v_lshl_add_u64 v[8:9], s[34:35], 0, v[94:95]
	v_add_co_u32_e32 v8, vcc, s11, v8
	v_addc_co_u32_e32 v9, vcc, 0, v9, vcc
	global_load_dwordx4 v[24:27], v[8:9], off
	global_load_dwordx4 v[20:23], v[8:9], off offset:256
	v_lshl_add_u64 v[8:9], s[34:35], 0, v[92:93]
	v_add_co_u32_e32 v10, vcc, s12, v8
	v_addc_co_u32_e32 v11, vcc, 0, v9, vcc
	global_load_dword v142, v[10:11], off
	v_add_co_u32_e32 v10, vcc, s13, v8
	v_addc_co_u32_e32 v11, vcc, 0, v9, vcc
	v_add_co_u32_e32 v8, vcc, s16, v8
	global_load_dword v143, v[10:11], off
	v_addc_co_u32_e32 v9, vcc, 0, v9, vcc
	global_load_dword v144, v[8:9], off
	v_lshl_add_u64 v[8:9], s[34:35], 0, v[90:91]
	v_add_co_u32_e32 v10, vcc, s17, v8
	v_addc_co_u32_e32 v11, vcc, 0, v9, vcc
	global_load_dwordx4 v[12:15], v[10:11], off
	v_add_co_u32_e32 v10, vcc, s18, v8
	v_addc_co_u32_e32 v11, vcc, 0, v9, vcc
	v_add_co_u32_e32 v8, vcc, s19, v8
	v_addc_co_u32_e32 v9, vcc, 0, v9, vcc
	global_load_dwordx4 v[16:19], v[10:11], off
	global_load_dwordx4 v[8:11], v[8:9], off
	v_lshl_add_u64 v[128:129], v[128:129], 0, s[6:7]
	s_nop 0
	v_lshl_add_u64 v[130:131], v[130:131], 0, s[8:9]
	s_nop 0
	s_nop 0
	v_lshl_add_u64 v[126:127], v[126:127], 0, s[4:5]
	s_nop 0
	s_cmpk_lt_i32 s10, 0x2000
	s_nop 0
	s_nop 0
	v_lshl_add_u64 v[116:117], v[116:117], 0, s[8:9]
	s_nop 0
	v_lshl_add_u64 v[114:115], v[114:115], 0, s[6:7]
	s_nop 0
	s_waitcnt vmcnt(31)
	v_lshlrev_b32_e32 v155, 16, v85
	s_nop 0
	v_lshlrev_b32_e32 v154, 16, v84
	s_nop 0
	s_waitcnt vmcnt(30)
	v_lshlrev_b32_e32 v157, 16, v81
	v_lshlrev_b32_e32 v156, 16, v80
	s_nop 0
	v_and_b32_e32 v85, 0xffff0000, v85
	v_and_b32_e32 v84, 0xffff0000, v84
	v_and_b32_e32 v81, 0xffff0000, v81
	v_and_b32_e32 v80, 0xffff0000, v80
	v_pk_fma_f32 v[154:155], v[122:123], v[156:157], v[154:155] neg_lo:[1,0,0] neg_hi:[1,0,0]
	v_pk_fma_f32 v[80:81], v[122:123], v[80:81], v[84:85] neg_lo:[1,0,0] neg_hi:[1,0,0]
	v_pk_mul_f32 v[84:85], v[154:155], v[154:155]
	v_pk_mul_f32 v[156:157], v[80:81], v[80:81]
	v_lshlrev_b32_e32 v159, 16, v87
	v_lshlrev_b32_e32 v158, 16, v86
	v_lshlrev_b32_e32 v161, 16, v83
	v_lshlrev_b32_e32 v160, 16, v82
	v_and_b32_e32 v87, 0xffff0000, v87
	v_and_b32_e32 v86, 0xffff0000, v86
	v_and_b32_e32 v83, 0xffff0000, v83
	v_and_b32_e32 v82, 0xffff0000, v82
	v_pk_fma_f32 v[158:159], v[122:123], v[160:161], v[158:159] neg_lo:[1,0,0] neg_hi:[1,0,0]
	v_pk_fma_f32 v[82:83], v[122:123], v[82:83], v[86:87] neg_lo:[1,0,0] neg_hi:[1,0,0]
	v_add_f32_e32 v84, v84, v156
	v_mov_b32_e32 v86, v82
	v_mov_b32_e32 v87, v158
	v_add_f32_e32 v84, v85, v84
	v_pk_mul_f32 v[86:87], v[86:87], v[86:87]
	v_add_f32_e32 v84, v157, v84
	v_mov_b32_e32 v160, v83
	v_mov_b32_e32 v161, v159
	v_add_f32_e32 v84, v87, v84
	v_pk_mul_f32 v[160:161], v[160:161], v[160:161]
	v_add_f32_e32 v84, v86, v84
	v_add_f32_e32 v84, v161, v84
	v_add_f32_e32 v84, v160, v84
	s_nop 0
	ds_bpermute_b32 v85, v136, v84
	s_waitcnt lgkmcnt(0)
	v_add_f32_e32 v84, v84, v85
	ds_bpermute_b32 v85, v137, v84
	s_nop 0
	s_nop 0
	s_waitcnt lgkmcnt(0)
	v_add_f32_e32 v84, v84, v85
	ds_bpermute_b32 v85, v138, v84
	s_nop 0
	s_waitcnt lgkmcnt(0)
	v_add_f32_e32 v84, v84, v85
	s_nop 0
	ds_bpermute_b32 v85, v139, v84
	v_lshl_add_u64 v[90:91], v[90:91], 0, s[4:5]
	s_nop 0
	s_waitcnt lgkmcnt(0)
	v_add_f32_e32 v84, v84, v85
	v_fmamk_f32 v84, v84, 0x3c000000, v140
	s_nop 0
	v_cmp_gt_f32_e32 vcc, s21, v84
	v_mul_f32_e32 v85, 0x4f800000, v84
	v_cndmask_b32_e32 v84, v84, v85, vcc
	v_sqrt_f32_e32 v85, v84
	v_lshl_add_u64 v[92:93], v[92:93], 0, s[6:7]
	v_lshl_add_u64 v[94:95], v[94:95], 0, s[8:9]
	v_add_u32_e32 v86, -1, v85
	v_fma_f32 v87, -v86, v85, v84
	v_cmp_ge_f32_e64 s[0:1], 0, v87
	v_add_u32_e32 v87, 1, v85
	v_lshl_add_u64 v[102:103], v[102:103], 0, s[4:5]
	v_cndmask_b32_e64 v86, v85, v86, s[0:1]
	v_fma_f32 v85, -v87, v85, v84
	v_cmp_lt_f32_e64 s[0:1], 0, v85
	v_lshl_add_u64 v[104:105], v[104:105], 0, s[6:7]
	v_lshl_add_u64 v[106:107], v[106:107], 0, s[8:9]
	v_cndmask_b32_e64 v85, v86, v87, s[0:1]
	v_mul_f32_e32 v86, 0x37800000, v85
	v_cndmask_b32_e32 v85, v85, v86, vcc
	v_cmp_class_f32_e32 vcc, v84, v141
	v_lshl_add_u64 v[112:113], v[112:113], 0, s[4:5]
	s_nop 0
	v_cndmask_b32_e32 v84, v85, v84, vcc
	v_div_scale_f32 v85, s[0:1], v84, v84, s22
	v_rcp_f32_e32 v86, v85
	s_nop 0
	v_fma_f32 v87, -v85, v86, 1.0
	v_fmac_f32_e32 v86, v87, v86
	v_div_scale_f32 v87, vcc, s22, v84, s22
	v_mul_f32_e32 v156, v87, v86
	v_fma_f32 v157, -v85, v156, v87
	v_fmac_f32_e32 v156, v157, v86
	v_fma_f32 v85, -v85, v156, v87
	v_div_fmas_f32 v85, v85, v86, v156
	v_div_fixup_f32 v84, v85, v84, s22
	v_pk_mul_f32 v[82:83], v[82:83], v[84:85] op_sel_hi:[1,0]
	v_pk_mul_f32 v[86:87], v[154:155], v[84:85] op_sel_hi:[1,0]
	v_pk_mul_f32 v[82:83], v[4:5], v[82:83]
	v_pk_mul_f32 v[86:87], v[2:3], v[86:87]
	v_pk_mul_f32 v[80:81], v[80:81], v[84:85] op_sel_hi:[1,0]
	v_pk_mul_f32 v[154:155], v[158:159], v[84:85] op_sel_hi:[1,0]
	v_bfe_u32 v84, v83, 16, 1
	v_bfe_u32 v85, v82, 16, 1
	v_pk_mul_f32 v[80:81], v[124:125], v[80:81]
	v_add3_u32 v82, v82, v85, s23
	v_add3_u32 v83, v83, v84, s23
	v_bfe_u32 v84, v86, 16, 1
	v_bfe_u32 v85, v87, 16, 1
	v_pk_mul_f32 v[154:155], v[6:7], v[154:155]
	v_bfe_u32 v156, v81, 16, 1
	v_bfe_u32 v157, v80, 16, 1
	v_add3_u32 v85, v87, v85, s23
	v_add3_u32 v84, v86, v84, s23
	v_add3_u32 v80, v80, v157, s23
	v_add3_u32 v81, v81, v156, s23
	v_bfe_u32 v156, v154, 16, 1
	v_bfe_u32 v157, v155, 16, 1
	v_lshrrev_b32_e32 v84, 16, v84
	v_lshrrev_b32_e32 v85, 16, v85
	v_add3_u32 v155, v155, v157, s23
	v_add3_u32 v154, v154, v156, s23
	v_and_or_b32 v81, v81, s20, v85
	v_and_or_b32 v80, v80, s20, v84
	v_lshl_add_u64 v[84:85], v[100:101], 0, v[134:135]
	v_lshrrev_b32_e32 v86, 16, v154
	v_lshrrev_b32_e32 v87, 16, v155
	v_add_co_u32_e32 v84, vcc, s24, v84
	v_and_or_b32 v83, v83, s20, v87
	v_and_or_b32 v82, v82, s20, v86
	v_addc_co_u32_e32 v85, vcc, -1, v85, vcc
	global_store_dwordx4 v[84:85], v[80:83], off offset:-256 sc1
	v_lshl_add_u64 v[134:135], v[134:135], 0, s[8:9]
	s_waitcnt vmcnt(28)
	v_max3_f32 v80, v151, v152, v153
	v_sub_f32_e32 v81, v151, v80
	v_exp_f32_e32 v83, v81
	v_sub_f32_e32 v81, v152, v80
	v_exp_f32_e32 v82, v81
	v_sub_f32_e32 v80, v153, v80
	v_exp_f32_e32 v80, v80
	v_add_f32_e32 v81, v83, v82
	v_add_f32_e32 v81, v80, v81
	v_div_scale_f32 v84, s[0:1], v81, v81, 1.0
	v_rcp_f32_e32 v85, v84
	s_nop 0
	v_fma_f32 v86, -v84, v85, 1.0
	v_fmac_f32_e32 v85, v86, v85
	v_div_scale_f32 v86, vcc, 1.0, v81, 1.0
	v_mul_f32_e32 v87, v86, v85
	v_fma_f32 v151, -v84, v87, v86
	v_fmac_f32_e32 v87, v151, v85
	v_fma_f32 v84, -v84, v87, v86
	v_div_fmas_f32 v84, v84, v85, v87
	v_div_fixup_f32 v84, v84, v81, 1.0
	v_pk_mul_f32 v[82:83], v[82:83], v[84:85] op_sel_hi:[1,0]
	s_waitcnt vmcnt(26)
	v_lshlrev_b32_e32 v87, 16, v77
	v_lshlrev_b32_e32 v86, 16, v72
	v_mul_f32_e32 v80, v80, v84
	v_lshlrev_b32_e32 v85, 16, v73
	v_lshlrev_b32_e32 v84, 16, v76
	v_pk_mul_f32 v[86:87], v[82:83], v[86:87] op_sel:[1,0] op_sel_hi:[0,1]
	v_pk_fma_f32 v[84:85], v[82:83], v[84:85], v[86:87]
	s_waitcnt vmcnt(25)
	v_lshlrev_b32_e32 v87, 16, v69
	v_lshlrev_b32_e32 v86, 16, v68
	v_pk_fma_f32 v[84:85], v[80:81], v[86:87], v[84:85] op_sel_hi:[0,1,1]
	v_and_b32_e32 v87, 0xffff0000, v73
	v_and_b32_e32 v73, 0xffff0000, v77
	v_and_b32_e32 v72, 0xffff0000, v72
	v_and_b32_e32 v86, 0xffff0000, v76
	v_pk_mul_f32 v[72:73], v[82:83], v[72:73] op_sel:[1,0] op_sel_hi:[0,1]
	v_pk_fma_f32 v[72:73], v[82:83], v[86:87], v[72:73]
	v_and_b32_e32 v69, 0xffff0000, v69
	v_and_b32_e32 v68, 0xffff0000, v68
	v_lshlrev_b32_e32 v77, 16, v79
	v_lshlrev_b32_e32 v76, 16, v74
	v_pk_fma_f32 v[68:69], v[80:81], v[68:69], v[72:73] op_sel_hi:[0,1,1]
	v_lshlrev_b32_e32 v73, 16, v75
	v_lshlrev_b32_e32 v72, 16, v78
	v_pk_mul_f32 v[76:77], v[82:83], v[76:77] op_sel:[1,0] op_sel_hi:[0,1]
	v_pk_fma_f32 v[72:73], v[82:83], v[72:73], v[76:77]
	v_lshlrev_b32_e32 v77, 16, v71
	v_lshlrev_b32_e32 v76, 16, v70
	v_pk_fma_f32 v[72:73], v[80:81], v[76:77], v[72:73] op_sel_hi:[0,1,1]
	v_and_b32_e32 v77, 0xffff0000, v75
	v_and_b32_e32 v75, 0xffff0000, v79
	v_and_b32_e32 v74, 0xffff0000, v74
	v_and_b32_e32 v76, 0xffff0000, v78
	v_pk_mul_f32 v[74:75], v[82:83], v[74:75] op_sel:[1,0] op_sel_hi:[0,1]
	v_pk_fma_f32 v[74:75], v[82:83], v[76:77], v[74:75]
	v_and_b32_e32 v71, 0xffff0000, v71
	v_and_b32_e32 v70, 0xffff0000, v70
	v_bfe_u32 v76, v69, 16, 1
	v_bfe_u32 v77, v68, 16, 1
	v_pk_fma_f32 v[70:71], v[80:81], v[70:71], v[74:75] op_sel_hi:[0,1,1]
	v_add3_u32 v68, v68, v77, s23
	v_add3_u32 v69, v69, v76, s23
	v_bfe_u32 v76, v72, 16, 1
	v_bfe_u32 v77, v73, 16, 1
	v_bfe_u32 v74, v71, 16, 1
	v_bfe_u32 v75, v70, 16, 1
	v_add3_u32 v73, v73, v77, s23
	v_add3_u32 v72, v72, v76, s23
	v_add3_u32 v70, v70, v75, s23
	v_add3_u32 v71, v71, v74, s23
	v_bfe_u32 v74, v84, 16, 1
	v_bfe_u32 v75, v85, 16, 1
	v_lshrrev_b32_e32 v72, 16, v72
	v_lshrrev_b32_e32 v73, 16, v73
	v_add3_u32 v75, v85, v75, s23
	v_add3_u32 v74, v84, v74, s23
	v_and_or_b32 v71, v71, s20, v73
	v_and_or_b32 v70, v70, s20, v72
	v_lshl_add_u64 v[72:73], v[88:89], 0, v[132:133]
	v_lshrrev_b32_e32 v74, 16, v74
	v_lshrrev_b32_e32 v75, 16, v75
	v_add_co_u32_e32 v72, vcc, s25, v72
	v_and_or_b32 v69, v69, s20, v75
	v_and_or_b32 v68, v68, s20, v74
	v_addc_co_u32_e32 v73, vcc, -1, v73, vcc
	global_store_dwordx4 v[72:73], v[68:71], off offset:-3072 sc1
	s_waitcnt vmcnt(25)
	v_lshlrev_b32_e32 v73, 16, v67
	v_lshlrev_b32_e32 v72, 16, v66
	v_lshlrev_b32_e32 v69, 16, v65
	v_lshlrev_b32_e32 v68, 16, v64
	s_waitcnt vmcnt(24)
	v_lshlrev_b32_e32 v71, 16, v61
	v_lshlrev_b32_e32 v70, 16, v60
	v_and_b32_e32 v65, 0xffff0000, v65
	v_and_b32_e32 v64, 0xffff0000, v64
	v_and_b32_e32 v61, 0xffff0000, v61
	v_and_b32_e32 v60, 0xffff0000, v60
	v_pk_fma_f32 v[68:69], v[122:123], v[70:71], v[68:69] neg_lo:[1,0,0] neg_hi:[1,0,0]
	v_pk_fma_f32 v[60:61], v[122:123], v[60:61], v[64:65] neg_lo:[1,0,0] neg_hi:[1,0,0]
	v_pk_mul_f32 v[64:65], v[68:69], v[68:69]
	v_pk_mul_f32 v[70:71], v[60:61], v[60:61]
	v_lshlrev_b32_e32 v75, 16, v63
	v_lshlrev_b32_e32 v74, 16, v62
	v_and_b32_e32 v67, 0xffff0000, v67
	v_and_b32_e32 v66, 0xffff0000, v66
	v_and_b32_e32 v63, 0xffff0000, v63
	v_and_b32_e32 v62, 0xffff0000, v62
	v_pk_fma_f32 v[72:73], v[122:123], v[74:75], v[72:73] neg_lo:[1,0,0] neg_hi:[1,0,0]
	v_pk_fma_f32 v[62:63], v[122:123], v[62:63], v[66:67] neg_lo:[1,0,0] neg_hi:[1,0,0]
	v_add_f32_e32 v64, v64, v70
	v_mov_b32_e32 v66, v62
	v_mov_b32_e32 v67, v72
	v_add_f32_e32 v64, v65, v64
	v_pk_mul_f32 v[66:67], v[66:67], v[66:67]
	v_add_f32_e32 v64, v71, v64
	v_mov_b32_e32 v74, v63
	v_mov_b32_e32 v75, v73
	v_add_f32_e32 v64, v67, v64
	v_pk_mul_f32 v[74:75], v[74:75], v[74:75]
	v_add_f32_e32 v64, v66, v64
	v_add_f32_e32 v64, v75, v64
	v_add_f32_e32 v64, v74, v64
	ds_bpermute_b32 v65, v136, v64
	v_lshl_add_u64 v[132:133], v[132:133], 0, s[8:9]
	s_waitcnt lgkmcnt(0)
	v_add_f32_e32 v64, v64, v65
	ds_bpermute_b32 v65, v137, v64
	s_waitcnt lgkmcnt(0)
	v_add_f32_e32 v64, v64, v65
	ds_bpermute_b32 v65, v138, v64
	s_waitcnt lgkmcnt(0)
	v_add_f32_e32 v64, v64, v65
	ds_bpermute_b32 v65, v139, v64
	s_waitcnt lgkmcnt(0)
	v_add_f32_e32 v64, v64, v65
	v_fmamk_f32 v64, v64, 0x3c000000, v140
	v_cmp_gt_f32_e32 vcc, s21, v64
	v_mul_f32_e32 v65, 0x4f800000, v64
	s_nop 0
	v_cndmask_b32_e32 v64, v64, v65, vcc
	v_sqrt_f32_e32 v65, v64
	s_nop 0
	v_add_u32_e32 v66, -1, v65
	v_fma_f32 v67, -v66, v65, v64
	v_cmp_ge_f32_e64 s[0:1], 0, v67
	v_add_u32_e32 v67, 1, v65
	s_nop 0
	v_cndmask_b32_e64 v66, v65, v66, s[0:1]
	v_fma_f32 v65, -v67, v65, v64
	v_cmp_lt_f32_e64 s[0:1], 0, v65
	s_nop 1
	v_cndmask_b32_e64 v65, v66, v67, s[0:1]
	v_mul_f32_e32 v66, 0x37800000, v65
	v_cndmask_b32_e32 v65, v65, v66, vcc
	v_cmp_class_f32_e32 vcc, v64, v141
	s_nop 1
	v_cndmask_b32_e32 v64, v65, v64, vcc
	v_div_scale_f32 v65, s[0:1], v64, v64, s22
	v_rcp_f32_e32 v66, v65
	s_nop 0
	v_fma_f32 v67, -v65, v66, 1.0
	v_fmac_f32_e32 v66, v67, v66
	v_div_scale_f32 v67, vcc, s22, v64, s22
	v_mul_f32_e32 v70, v67, v66
	v_fma_f32 v71, -v65, v70, v67
	v_fmac_f32_e32 v70, v71, v66
	v_fma_f32 v65, -v65, v70, v67
	v_div_fmas_f32 v65, v65, v66, v70
	v_div_fixup_f32 v64, v65, v64, s22
	v_pk_mul_f32 v[62:63], v[62:63], v[64:65] op_sel_hi:[1,0]
	v_pk_mul_f32 v[66:67], v[68:69], v[64:65] op_sel_hi:[1,0]
	v_pk_mul_f32 v[62:63], v[4:5], v[62:63]
	v_pk_mul_f32 v[66:67], v[2:3], v[66:67]
	v_pk_mul_f32 v[60:61], v[60:61], v[64:65] op_sel_hi:[1,0]
	v_pk_mul_f32 v[68:69], v[72:73], v[64:65] op_sel_hi:[1,0]
	v_bfe_u32 v64, v63, 16, 1
	v_bfe_u32 v65, v62, 16, 1
	v_pk_mul_f32 v[60:61], v[124:125], v[60:61]
	v_add3_u32 v62, v62, v65, s23
	v_add3_u32 v63, v63, v64, s23
	v_bfe_u32 v64, v66, 16, 1
	v_bfe_u32 v65, v67, 16, 1
	v_pk_mul_f32 v[68:69], v[6:7], v[68:69]
	v_bfe_u32 v70, v61, 16, 1
	v_bfe_u32 v71, v60, 16, 1
	v_add3_u32 v65, v67, v65, s23
	v_add3_u32 v64, v66, v64, s23
	v_add3_u32 v60, v60, v71, s23
	v_add3_u32 v61, v61, v70, s23
	v_bfe_u32 v70, v68, 16, 1
	v_bfe_u32 v71, v69, 16, 1
	v_lshrrev_b32_e32 v64, 16, v64
	v_lshrrev_b32_e32 v65, 16, v65
	v_add3_u32 v69, v69, v71, s23
	v_add3_u32 v68, v68, v70, s23
	v_and_or_b32 v61, v61, s20, v65
	v_and_or_b32 v60, v60, s20, v64
	v_lshl_add_u64 v[64:65], v[100:101], 0, v[120:121]
	v_lshrrev_b32_e32 v66, 16, v68
	v_lshrrev_b32_e32 v67, 16, v69
	v_add_co_u32_e32 v64, vcc, s24, v64
	v_and_or_b32 v63, v63, s20, v67
	v_and_or_b32 v62, v62, s20, v66
	v_addc_co_u32_e32 v65, vcc, -1, v65, vcc
	global_store_dwordx4 v[64:65], v[60:63], off offset:-256 sc1
	v_lshl_add_u64 v[120:121], v[120:121], 0, s[8:9]
	s_waitcnt vmcnt(22)
	v_max3_f32 v60, v148, v149, v150
	v_sub_f32_e32 v61, v148, v60
	v_exp_f32_e32 v63, v61
	v_sub_f32_e32 v61, v149, v60
	v_exp_f32_e32 v62, v61
	v_sub_f32_e32 v60, v150, v60
	v_exp_f32_e32 v60, v60
	v_add_f32_e32 v61, v63, v62
	v_add_f32_e32 v61, v60, v61
	v_div_scale_f32 v64, s[0:1], v61, v61, 1.0
	v_rcp_f32_e32 v65, v64
	s_nop 0
	v_fma_f32 v66, -v64, v65, 1.0
	v_fmac_f32_e32 v65, v66, v65
	v_div_scale_f32 v66, vcc, 1.0, v61, 1.0
	v_mul_f32_e32 v67, v66, v65
	v_fma_f32 v68, -v64, v67, v66
	v_fmac_f32_e32 v67, v68, v65
	v_fma_f32 v64, -v64, v67, v66
	v_div_fmas_f32 v64, v64, v65, v67
	v_div_fixup_f32 v64, v64, v61, 1.0
	v_pk_mul_f32 v[62:63], v[62:63], v[64:65] op_sel_hi:[1,0]
	s_waitcnt vmcnt(20)
	v_lshlrev_b32_e32 v67, 16, v57
	v_lshlrev_b32_e32 v66, 16, v52
	v_mul_f32_e32 v60, v60, v64
	v_lshlrev_b32_e32 v65, 16, v53
	v_lshlrev_b32_e32 v64, 16, v56
	v_pk_mul_f32 v[66:67], v[62:63], v[66:67] op_sel:[1,0] op_sel_hi:[0,1]
	v_pk_fma_f32 v[64:65], v[62:63], v[64:65], v[66:67]
	s_waitcnt vmcnt(19)
	v_lshlrev_b32_e32 v67, 16, v49
	v_lshlrev_b32_e32 v66, 16, v48
	v_pk_fma_f32 v[64:65], v[60:61], v[66:67], v[64:65] op_sel_hi:[0,1,1]
	v_and_b32_e32 v67, 0xffff0000, v53
	v_and_b32_e32 v53, 0xffff0000, v57
	v_and_b32_e32 v52, 0xffff0000, v52
	v_and_b32_e32 v66, 0xffff0000, v56
	v_pk_mul_f32 v[52:53], v[62:63], v[52:53] op_sel:[1,0] op_sel_hi:[0,1]
	v_pk_fma_f32 v[52:53], v[62:63], v[66:67], v[52:53]
	v_and_b32_e32 v49, 0xffff0000, v49
	v_and_b32_e32 v48, 0xffff0000, v48
	v_lshlrev_b32_e32 v57, 16, v59
	v_lshlrev_b32_e32 v56, 16, v54
	v_pk_fma_f32 v[48:49], v[60:61], v[48:49], v[52:53] op_sel_hi:[0,1,1]
	v_lshlrev_b32_e32 v53, 16, v55
	v_lshlrev_b32_e32 v52, 16, v58
	v_pk_mul_f32 v[56:57], v[62:63], v[56:57] op_sel:[1,0] op_sel_hi:[0,1]
	v_pk_fma_f32 v[52:53], v[62:63], v[52:53], v[56:57]
	v_lshlrev_b32_e32 v57, 16, v51
	v_lshlrev_b32_e32 v56, 16, v50
	v_pk_fma_f32 v[52:53], v[60:61], v[56:57], v[52:53] op_sel_hi:[0,1,1]
	v_and_b32_e32 v57, 0xffff0000, v55
	v_and_b32_e32 v55, 0xffff0000, v59
	v_and_b32_e32 v54, 0xffff0000, v54
	v_and_b32_e32 v56, 0xffff0000, v58
	v_pk_mul_f32 v[54:55], v[62:63], v[54:55] op_sel:[1,0] op_sel_hi:[0,1]
	v_pk_fma_f32 v[54:55], v[62:63], v[56:57], v[54:55]
	v_and_b32_e32 v51, 0xffff0000, v51
	v_and_b32_e32 v50, 0xffff0000, v50
	v_bfe_u32 v56, v49, 16, 1
	v_bfe_u32 v57, v48, 16, 1
	v_pk_fma_f32 v[50:51], v[60:61], v[50:51], v[54:55] op_sel_hi:[0,1,1]
	v_add3_u32 v48, v48, v57, s23
	v_add3_u32 v49, v49, v56, s23
	v_bfe_u32 v56, v52, 16, 1
	v_bfe_u32 v57, v53, 16, 1
	v_bfe_u32 v54, v51, 16, 1
	v_bfe_u32 v55, v50, 16, 1
	v_add3_u32 v53, v53, v57, s23
	v_add3_u32 v52, v52, v56, s23
	v_add3_u32 v50, v50, v55, s23
	v_add3_u32 v51, v51, v54, s23
	v_bfe_u32 v54, v64, 16, 1
	v_bfe_u32 v55, v65, 16, 1
	v_lshrrev_b32_e32 v52, 16, v52
	v_lshrrev_b32_e32 v53, 16, v53
	v_add3_u32 v55, v65, v55, s23
	v_add3_u32 v54, v64, v54, s23
	v_and_or_b32 v51, v51, s20, v53
	v_and_or_b32 v50, v50, s20, v52
	v_lshl_add_u64 v[52:53], v[88:89], 0, v[118:119]
	v_lshrrev_b32_e32 v54, 16, v54
	v_lshrrev_b32_e32 v55, 16, v55
	v_add_co_u32_e32 v52, vcc, s25, v52
	v_and_or_b32 v49, v49, s20, v55
	v_and_or_b32 v48, v48, s20, v54
	v_addc_co_u32_e32 v53, vcc, -1, v53, vcc
	global_store_dwordx4 v[52:53], v[48:51], off offset:-3072 sc1
	s_waitcnt vmcnt(19)
	v_lshlrev_b32_e32 v53, 16, v47
	v_lshlrev_b32_e32 v52, 16, v46
	v_lshlrev_b32_e32 v49, 16, v45
	v_lshlrev_b32_e32 v48, 16, v44
	s_waitcnt vmcnt(18)
	v_lshlrev_b32_e32 v51, 16, v41
	v_lshlrev_b32_e32 v50, 16, v40
	v_and_b32_e32 v45, 0xffff0000, v45
	v_and_b32_e32 v44, 0xffff0000, v44
	v_and_b32_e32 v41, 0xffff0000, v41
	v_and_b32_e32 v40, 0xffff0000, v40
	v_pk_fma_f32 v[48:49], v[122:123], v[50:51], v[48:49] neg_lo:[1,0,0] neg_hi:[1,0,0]
	v_pk_fma_f32 v[40:41], v[122:123], v[40:41], v[44:45] neg_lo:[1,0,0] neg_hi:[1,0,0]
	v_pk_mul_f32 v[44:45], v[48:49], v[48:49]
	v_pk_mul_f32 v[50:51], v[40:41], v[40:41]
	v_lshlrev_b32_e32 v55, 16, v43
	v_lshlrev_b32_e32 v54, 16, v42
	v_and_b32_e32 v47, 0xffff0000, v47
	v_and_b32_e32 v46, 0xffff0000, v46
	v_and_b32_e32 v43, 0xffff0000, v43
	v_and_b32_e32 v42, 0xffff0000, v42
	v_pk_fma_f32 v[52:53], v[122:123], v[54:55], v[52:53] neg_lo:[1,0,0] neg_hi:[1,0,0]
	v_pk_fma_f32 v[42:43], v[122:123], v[42:43], v[46:47] neg_lo:[1,0,0] neg_hi:[1,0,0]
	v_add_f32_e32 v44, v44, v50
	v_mov_b32_e32 v46, v42
	v_mov_b32_e32 v47, v52
	v_add_f32_e32 v44, v45, v44
	v_pk_mul_f32 v[46:47], v[46:47], v[46:47]
	v_add_f32_e32 v44, v51, v44
	v_mov_b32_e32 v54, v43
	v_mov_b32_e32 v55, v53
	v_add_f32_e32 v44, v47, v44
	v_pk_mul_f32 v[54:55], v[54:55], v[54:55]
	v_add_f32_e32 v44, v46, v44
	v_add_f32_e32 v44, v55, v44
	v_add_f32_e32 v44, v54, v44
	ds_bpermute_b32 v45, v136, v44
	v_lshl_add_u64 v[118:119], v[118:119], 0, s[8:9]
	s_waitcnt lgkmcnt(0)
	v_add_f32_e32 v44, v44, v45
	ds_bpermute_b32 v45, v137, v44
	s_waitcnt lgkmcnt(0)
	v_add_f32_e32 v44, v44, v45
	ds_bpermute_b32 v45, v138, v44
	s_waitcnt lgkmcnt(0)
	v_add_f32_e32 v44, v44, v45
	ds_bpermute_b32 v45, v139, v44
	s_waitcnt lgkmcnt(0)
	v_add_f32_e32 v44, v44, v45
	v_fmamk_f32 v44, v44, 0x3c000000, v140
	v_cmp_gt_f32_e32 vcc, s21, v44
	v_mul_f32_e32 v45, 0x4f800000, v44
	s_nop 0
	v_cndmask_b32_e32 v44, v44, v45, vcc
	v_sqrt_f32_e32 v45, v44
	s_nop 0
	v_add_u32_e32 v46, -1, v45
	v_fma_f32 v47, -v46, v45, v44
	v_cmp_ge_f32_e64 s[0:1], 0, v47
	v_add_u32_e32 v47, 1, v45
	s_nop 0
	v_cndmask_b32_e64 v46, v45, v46, s[0:1]
	v_fma_f32 v45, -v47, v45, v44
	v_cmp_lt_f32_e64 s[0:1], 0, v45
	s_nop 1
	v_cndmask_b32_e64 v45, v46, v47, s[0:1]
	v_mul_f32_e32 v46, 0x37800000, v45
	v_cndmask_b32_e32 v45, v45, v46, vcc
	v_cmp_class_f32_e32 vcc, v44, v141
	s_nop 1
	v_cndmask_b32_e32 v44, v45, v44, vcc
	v_div_scale_f32 v45, s[0:1], v44, v44, s22
	v_rcp_f32_e32 v46, v45
	s_nop 0
	v_fma_f32 v47, -v45, v46, 1.0
	v_fmac_f32_e32 v46, v47, v46
	v_div_scale_f32 v47, vcc, s22, v44, s22
	v_mul_f32_e32 v50, v47, v46
	v_fma_f32 v51, -v45, v50, v47
	v_fmac_f32_e32 v50, v51, v46
	v_fma_f32 v45, -v45, v50, v47
	v_div_fmas_f32 v45, v45, v46, v50
	v_div_fixup_f32 v44, v45, v44, s22
	v_pk_mul_f32 v[42:43], v[42:43], v[44:45] op_sel_hi:[1,0]
	v_pk_mul_f32 v[46:47], v[48:49], v[44:45] op_sel_hi:[1,0]
	v_pk_mul_f32 v[42:43], v[4:5], v[42:43]
	v_pk_mul_f32 v[46:47], v[2:3], v[46:47]
	v_pk_mul_f32 v[40:41], v[40:41], v[44:45] op_sel_hi:[1,0]
	v_pk_mul_f32 v[48:49], v[52:53], v[44:45] op_sel_hi:[1,0]
	v_bfe_u32 v44, v43, 16, 1
	v_bfe_u32 v45, v42, 16, 1
	v_pk_mul_f32 v[40:41], v[124:125], v[40:41]
	v_add3_u32 v42, v42, v45, s23
	v_add3_u32 v43, v43, v44, s23
	v_bfe_u32 v44, v46, 16, 1
	v_bfe_u32 v45, v47, 16, 1
	v_pk_mul_f32 v[48:49], v[6:7], v[48:49]
	v_bfe_u32 v50, v41, 16, 1
	v_bfe_u32 v51, v40, 16, 1
	v_add3_u32 v45, v47, v45, s23
	v_add3_u32 v44, v46, v44, s23
	v_add3_u32 v40, v40, v51, s23
	v_add3_u32 v41, v41, v50, s23
	v_bfe_u32 v50, v48, 16, 1
	v_bfe_u32 v51, v49, 16, 1
	v_lshrrev_b32_e32 v44, 16, v44
	v_lshrrev_b32_e32 v45, 16, v45
	v_add3_u32 v49, v49, v51, s23
	v_add3_u32 v48, v48, v50, s23
	v_and_or_b32 v41, v41, s20, v45
	v_and_or_b32 v40, v40, s20, v44
	v_lshl_add_u64 v[44:45], v[100:101], 0, v[110:111]
	v_lshrrev_b32_e32 v46, 16, v48
	v_lshrrev_b32_e32 v47, 16, v49
	v_add_co_u32_e32 v44, vcc, s24, v44
	v_and_or_b32 v43, v43, s20, v47
	v_and_or_b32 v42, v42, s20, v46
	v_addc_co_u32_e32 v45, vcc, -1, v45, vcc
	global_store_dwordx4 v[44:45], v[40:43], off offset:-256 sc1
	v_lshl_add_u64 v[110:111], v[110:111], 0, s[8:9]
	s_waitcnt vmcnt(16)
	v_max3_f32 v40, v145, v146, v147
	v_sub_f32_e32 v41, v145, v40
	v_exp_f32_e32 v43, v41
	v_sub_f32_e32 v41, v146, v40
	v_exp_f32_e32 v42, v41
	v_sub_f32_e32 v40, v147, v40
	v_exp_f32_e32 v40, v40
	v_add_f32_e32 v41, v43, v42
	v_add_f32_e32 v41, v40, v41
	v_div_scale_f32 v44, s[0:1], v41, v41, 1.0
	v_rcp_f32_e32 v45, v44
	s_nop 0
	v_fma_f32 v46, -v44, v45, 1.0
	v_fmac_f32_e32 v45, v46, v45
	v_div_scale_f32 v46, vcc, 1.0, v41, 1.0
	v_mul_f32_e32 v47, v46, v45
	v_fma_f32 v48, -v44, v47, v46
	v_fmac_f32_e32 v47, v48, v45
	v_fma_f32 v44, -v44, v47, v46
	v_div_fmas_f32 v44, v44, v45, v47
	v_div_fixup_f32 v44, v44, v41, 1.0
	v_pk_mul_f32 v[42:43], v[42:43], v[44:45] op_sel_hi:[1,0]
	s_waitcnt vmcnt(14)
	v_lshlrev_b32_e32 v47, 16, v37
	v_lshlrev_b32_e32 v46, 16, v32
	v_mul_f32_e32 v40, v40, v44
	v_lshlrev_b32_e32 v45, 16, v33
	v_lshlrev_b32_e32 v44, 16, v36
	v_pk_mul_f32 v[46:47], v[42:43], v[46:47] op_sel:[1,0] op_sel_hi:[0,1]
	v_pk_fma_f32 v[44:45], v[42:43], v[44:45], v[46:47]
	s_waitcnt vmcnt(13)
	v_lshlrev_b32_e32 v47, 16, v29
	v_lshlrev_b32_e32 v46, 16, v28
	v_pk_fma_f32 v[44:45], v[40:41], v[46:47], v[44:45] op_sel_hi:[0,1,1]
	v_and_b32_e32 v47, 0xffff0000, v33
	v_and_b32_e32 v33, 0xffff0000, v37
	v_and_b32_e32 v32, 0xffff0000, v32
	v_and_b32_e32 v46, 0xffff0000, v36
	v_pk_mul_f32 v[32:33], v[42:43], v[32:33] op_sel:[1,0] op_sel_hi:[0,1]
	v_pk_fma_f32 v[32:33], v[42:43], v[46:47], v[32:33]
	v_and_b32_e32 v29, 0xffff0000, v29
	v_and_b32_e32 v28, 0xffff0000, v28
	v_lshlrev_b32_e32 v37, 16, v39
	v_lshlrev_b32_e32 v36, 16, v34
	v_pk_fma_f32 v[28:29], v[40:41], v[28:29], v[32:33] op_sel_hi:[0,1,1]
	v_lshlrev_b32_e32 v33, 16, v35
	v_lshlrev_b32_e32 v32, 16, v38
	v_pk_mul_f32 v[36:37], v[42:43], v[36:37] op_sel:[1,0] op_sel_hi:[0,1]
	v_pk_fma_f32 v[32:33], v[42:43], v[32:33], v[36:37]
	v_lshlrev_b32_e32 v37, 16, v31
	v_lshlrev_b32_e32 v36, 16, v30
	v_pk_fma_f32 v[32:33], v[40:41], v[36:37], v[32:33] op_sel_hi:[0,1,1]
	v_and_b32_e32 v37, 0xffff0000, v35
	v_and_b32_e32 v35, 0xffff0000, v39
	v_and_b32_e32 v34, 0xffff0000, v34
	v_and_b32_e32 v36, 0xffff0000, v38
	v_pk_mul_f32 v[34:35], v[42:43], v[34:35] op_sel:[1,0] op_sel_hi:[0,1]
	v_pk_fma_f32 v[34:35], v[42:43], v[36:37], v[34:35]
	v_and_b32_e32 v31, 0xffff0000, v31
	v_and_b32_e32 v30, 0xffff0000, v30
	v_bfe_u32 v36, v29, 16, 1
	v_bfe_u32 v37, v28, 16, 1
	v_pk_fma_f32 v[30:31], v[40:41], v[30:31], v[34:35] op_sel_hi:[0,1,1]
	v_add3_u32 v28, v28, v37, s23
	v_add3_u32 v29, v29, v36, s23
	v_bfe_u32 v36, v32, 16, 1
	v_bfe_u32 v37, v33, 16, 1
	v_bfe_u32 v34, v31, 16, 1
	v_bfe_u32 v35, v30, 16, 1
	v_add3_u32 v33, v33, v37, s23
	v_add3_u32 v32, v32, v36, s23
	v_add3_u32 v30, v30, v35, s23
	v_add3_u32 v31, v31, v34, s23
	v_bfe_u32 v34, v44, 16, 1
	v_bfe_u32 v35, v45, 16, 1
	v_lshrrev_b32_e32 v32, 16, v32
	v_lshrrev_b32_e32 v33, 16, v33
	v_add3_u32 v35, v45, v35, s23
	v_add3_u32 v34, v44, v34, s23
	v_and_or_b32 v31, v31, s20, v33
	v_and_or_b32 v30, v30, s20, v32
	v_lshl_add_u64 v[32:33], v[88:89], 0, v[108:109]
	v_lshrrev_b32_e32 v34, 16, v34
	v_lshrrev_b32_e32 v35, 16, v35
	v_add_co_u32_e32 v32, vcc, s25, v32
	v_and_or_b32 v29, v29, s20, v35
	v_and_or_b32 v28, v28, s20, v34
	v_addc_co_u32_e32 v33, vcc, -1, v33, vcc
	global_store_dwordx4 v[32:33], v[28:31], off offset:-3072 sc1
	s_waitcnt vmcnt(13)
	v_lshlrev_b32_e32 v33, 16, v27
	v_lshlrev_b32_e32 v32, 16, v26
	v_lshlrev_b32_e32 v29, 16, v25
	v_lshlrev_b32_e32 v28, 16, v24
	s_waitcnt vmcnt(12)
	v_lshlrev_b32_e32 v31, 16, v21
	v_lshlrev_b32_e32 v30, 16, v20
	v_and_b32_e32 v25, 0xffff0000, v25
	v_and_b32_e32 v24, 0xffff0000, v24
	v_and_b32_e32 v21, 0xffff0000, v21
	v_and_b32_e32 v20, 0xffff0000, v20
	v_pk_fma_f32 v[28:29], v[122:123], v[30:31], v[28:29] neg_lo:[1,0,0] neg_hi:[1,0,0]
	v_pk_fma_f32 v[20:21], v[122:123], v[20:21], v[24:25] neg_lo:[1,0,0] neg_hi:[1,0,0]
	v_pk_mul_f32 v[24:25], v[28:29], v[28:29]
	v_pk_mul_f32 v[30:31], v[20:21], v[20:21]
	v_lshlrev_b32_e32 v35, 16, v23
	v_lshlrev_b32_e32 v34, 16, v22
	v_and_b32_e32 v27, 0xffff0000, v27
	v_and_b32_e32 v26, 0xffff0000, v26
	v_and_b32_e32 v23, 0xffff0000, v23
	v_and_b32_e32 v22, 0xffff0000, v22
	v_pk_fma_f32 v[32:33], v[122:123], v[34:35], v[32:33] neg_lo:[1,0,0] neg_hi:[1,0,0]
	v_pk_fma_f32 v[22:23], v[122:123], v[22:23], v[26:27] neg_lo:[1,0,0] neg_hi:[1,0,0]
	v_add_f32_e32 v24, v24, v30
	v_mov_b32_e32 v26, v22
	v_mov_b32_e32 v27, v32
	v_add_f32_e32 v24, v25, v24
	v_pk_mul_f32 v[26:27], v[26:27], v[26:27]
	v_add_f32_e32 v24, v31, v24
	v_mov_b32_e32 v34, v23
	v_mov_b32_e32 v35, v33
	v_add_f32_e32 v24, v27, v24
	v_pk_mul_f32 v[34:35], v[34:35], v[34:35]
	v_add_f32_e32 v24, v26, v24
	v_add_f32_e32 v24, v35, v24
	v_add_f32_e32 v24, v34, v24
	ds_bpermute_b32 v25, v136, v24
	v_lshl_add_u64 v[108:109], v[108:109], 0, s[8:9]
	s_waitcnt lgkmcnt(0)
	v_add_f32_e32 v24, v24, v25
	ds_bpermute_b32 v25, v137, v24
	s_waitcnt lgkmcnt(0)
	v_add_f32_e32 v24, v24, v25
	ds_bpermute_b32 v25, v138, v24
	s_waitcnt lgkmcnt(0)
	v_add_f32_e32 v24, v24, v25
	ds_bpermute_b32 v25, v139, v24
	s_waitcnt lgkmcnt(0)
	v_add_f32_e32 v24, v24, v25
	v_fmamk_f32 v24, v24, 0x3c000000, v140
	v_cmp_gt_f32_e32 vcc, s21, v24
	v_mul_f32_e32 v25, 0x4f800000, v24
	s_nop 0
	v_cndmask_b32_e32 v24, v24, v25, vcc
	v_sqrt_f32_e32 v25, v24
	s_nop 0
	v_add_u32_e32 v26, -1, v25
	v_fma_f32 v27, -v26, v25, v24
	v_cmp_ge_f32_e64 s[0:1], 0, v27
	v_add_u32_e32 v27, 1, v25
	s_nop 0
	v_cndmask_b32_e64 v26, v25, v26, s[0:1]
	v_fma_f32 v25, -v27, v25, v24
	v_cmp_lt_f32_e64 s[0:1], 0, v25
	s_nop 1
	v_cndmask_b32_e64 v25, v26, v27, s[0:1]
	v_mul_f32_e32 v26, 0x37800000, v25
	v_cndmask_b32_e32 v25, v25, v26, vcc
	v_cmp_class_f32_e32 vcc, v24, v141
	s_nop 1
	v_cndmask_b32_e32 v24, v25, v24, vcc
	v_div_scale_f32 v25, s[0:1], v24, v24, s22
	v_rcp_f32_e32 v26, v25
	s_nop 0
	v_fma_f32 v27, -v25, v26, 1.0
	v_fmac_f32_e32 v26, v27, v26
	v_div_scale_f32 v27, vcc, s22, v24, s22
	v_mul_f32_e32 v30, v27, v26
	v_fma_f32 v31, -v25, v30, v27
	v_fmac_f32_e32 v30, v31, v26
	v_fma_f32 v25, -v25, v30, v27
	v_div_fmas_f32 v25, v25, v26, v30
	v_div_fixup_f32 v24, v25, v24, s22
	v_pk_mul_f32 v[22:23], v[22:23], v[24:25] op_sel_hi:[1,0]
	v_pk_mul_f32 v[26:27], v[28:29], v[24:25] op_sel_hi:[1,0]
	v_pk_mul_f32 v[22:23], v[4:5], v[22:23]
	v_pk_mul_f32 v[26:27], v[2:3], v[26:27]
	v_pk_mul_f32 v[20:21], v[20:21], v[24:25] op_sel_hi:[1,0]
	v_pk_mul_f32 v[28:29], v[32:33], v[24:25] op_sel_hi:[1,0]
	v_bfe_u32 v24, v23, 16, 1
	v_bfe_u32 v25, v22, 16, 1
	v_pk_mul_f32 v[20:21], v[124:125], v[20:21]
	v_add3_u32 v22, v22, v25, s23
	v_add3_u32 v23, v23, v24, s23
	v_bfe_u32 v24, v26, 16, 1
	v_bfe_u32 v25, v27, 16, 1
	v_pk_mul_f32 v[28:29], v[6:7], v[28:29]
	v_bfe_u32 v30, v21, 16, 1
	v_bfe_u32 v31, v20, 16, 1
	v_add3_u32 v25, v27, v25, s23
	v_add3_u32 v24, v26, v24, s23
	v_add3_u32 v20, v20, v31, s23
	v_add3_u32 v21, v21, v30, s23
	v_bfe_u32 v30, v28, 16, 1
	v_bfe_u32 v31, v29, 16, 1
	v_lshrrev_b32_e32 v24, 16, v24
	v_lshrrev_b32_e32 v25, 16, v25
	v_add3_u32 v29, v29, v31, s23
	v_add3_u32 v28, v28, v30, s23
	v_and_or_b32 v21, v21, s20, v25
	v_and_or_b32 v20, v20, s20, v24
	v_lshl_add_u64 v[24:25], v[100:101], 0, v[98:99]
	v_lshrrev_b32_e32 v26, 16, v28
	v_lshrrev_b32_e32 v27, 16, v29
	v_add_co_u32_e32 v24, vcc, s24, v24
	v_and_or_b32 v23, v23, s20, v27
	v_and_or_b32 v22, v22, s20, v26
	v_addc_co_u32_e32 v25, vcc, -1, v25, vcc
	global_store_dwordx4 v[24:25], v[20:23], off offset:-256 sc1
	v_lshl_add_u64 v[98:99], v[98:99], 0, s[8:9]
	s_waitcnt vmcnt(10)
	v_max3_f32 v20, v142, v143, v144
	v_sub_f32_e32 v21, v142, v20
	v_exp_f32_e32 v23, v21
	v_sub_f32_e32 v21, v143, v20
	v_exp_f32_e32 v22, v21
	v_sub_f32_e32 v20, v144, v20
	v_exp_f32_e32 v20, v20
	v_add_f32_e32 v21, v23, v22
	v_add_f32_e32 v21, v20, v21
	v_div_scale_f32 v24, s[0:1], v21, v21, 1.0
	v_rcp_f32_e32 v25, v24
	s_nop 0
	v_fma_f32 v26, -v24, v25, 1.0
	v_fmac_f32_e32 v25, v26, v25
	v_div_scale_f32 v26, vcc, 1.0, v21, 1.0
	v_mul_f32_e32 v27, v26, v25
	v_fma_f32 v28, -v24, v27, v26
	v_fmac_f32_e32 v27, v28, v25
	v_fma_f32 v24, -v24, v27, v26
	v_div_fmas_f32 v24, v24, v25, v27
	v_div_fixup_f32 v24, v24, v21, 1.0
	v_pk_mul_f32 v[22:23], v[22:23], v[24:25] op_sel_hi:[1,0]
	s_waitcnt vmcnt(8)
	v_lshlrev_b32_e32 v27, 16, v17
	v_lshlrev_b32_e32 v26, 16, v12
	v_mul_f32_e32 v20, v20, v24
	v_lshlrev_b32_e32 v25, 16, v13
	v_lshlrev_b32_e32 v24, 16, v16
	v_pk_mul_f32 v[26:27], v[22:23], v[26:27] op_sel:[1,0] op_sel_hi:[0,1]
	v_pk_fma_f32 v[24:25], v[22:23], v[24:25], v[26:27]
	s_waitcnt vmcnt(7)
	v_lshlrev_b32_e32 v27, 16, v9
	v_lshlrev_b32_e32 v26, 16, v8
	v_pk_fma_f32 v[24:25], v[20:21], v[26:27], v[24:25] op_sel_hi:[0,1,1]
	v_and_b32_e32 v27, 0xffff0000, v13
	v_and_b32_e32 v13, 0xffff0000, v17
	v_and_b32_e32 v12, 0xffff0000, v12
	v_and_b32_e32 v26, 0xffff0000, v16
	v_pk_mul_f32 v[12:13], v[22:23], v[12:13] op_sel:[1,0] op_sel_hi:[0,1]
	v_pk_fma_f32 v[12:13], v[22:23], v[26:27], v[12:13]
	v_and_b32_e32 v9, 0xffff0000, v9
	v_and_b32_e32 v8, 0xffff0000, v8
	v_lshlrev_b32_e32 v17, 16, v19
	v_lshlrev_b32_e32 v16, 16, v14
	v_pk_fma_f32 v[8:9], v[20:21], v[8:9], v[12:13] op_sel_hi:[0,1,1]
	v_lshlrev_b32_e32 v13, 16, v15
	v_lshlrev_b32_e32 v12, 16, v18
	v_pk_mul_f32 v[16:17], v[22:23], v[16:17] op_sel:[1,0] op_sel_hi:[0,1]
	v_pk_fma_f32 v[12:13], v[22:23], v[12:13], v[16:17]
	v_lshlrev_b32_e32 v17, 16, v11
	v_lshlrev_b32_e32 v16, 16, v10
	v_pk_fma_f32 v[12:13], v[20:21], v[16:17], v[12:13] op_sel_hi:[0,1,1]
	v_and_b32_e32 v17, 0xffff0000, v15
	v_and_b32_e32 v15, 0xffff0000, v19
	v_and_b32_e32 v14, 0xffff0000, v14
	v_and_b32_e32 v16, 0xffff0000, v18
	v_pk_mul_f32 v[14:15], v[22:23], v[14:15] op_sel:[1,0] op_sel_hi:[0,1]
	v_pk_fma_f32 v[14:15], v[22:23], v[16:17], v[14:15]
	v_and_b32_e32 v11, 0xffff0000, v11
	v_and_b32_e32 v10, 0xffff0000, v10
	v_bfe_u32 v16, v9, 16, 1
	v_bfe_u32 v17, v8, 16, 1
	v_pk_fma_f32 v[10:11], v[20:21], v[10:11], v[14:15] op_sel_hi:[0,1,1]
	v_add3_u32 v8, v8, v17, s23
	v_add3_u32 v9, v9, v16, s23
	v_bfe_u32 v16, v12, 16, 1
	v_bfe_u32 v17, v13, 16, 1
	v_bfe_u32 v14, v11, 16, 1
	v_bfe_u32 v15, v10, 16, 1
	v_add3_u32 v13, v13, v17, s23
	v_add3_u32 v12, v12, v16, s23
	v_add3_u32 v10, v10, v15, s23
	v_add3_u32 v11, v11, v14, s23
	v_bfe_u32 v14, v24, 16, 1
	v_bfe_u32 v15, v25, 16, 1
	v_lshrrev_b32_e32 v12, 16, v12
	v_lshrrev_b32_e32 v13, 16, v13
	v_add3_u32 v15, v25, v15, s23
	v_add3_u32 v14, v24, v14, s23
	v_and_or_b32 v11, v11, s20, v13
	v_and_or_b32 v10, v10, s20, v12
	v_lshl_add_u64 v[12:13], v[88:89], 0, v[96:97]
	v_lshrrev_b32_e32 v14, 16, v14
	v_lshrrev_b32_e32 v15, 16, v15
	v_add_co_u32_e32 v12, vcc, s25, v12
	v_and_or_b32 v9, v9, s20, v15
	v_and_or_b32 v8, v8, s20, v14
	v_addc_co_u32_e32 v13, vcc, -1, v13, vcc
	v_lshl_add_u64 v[96:97], v[96:97], 0, s[8:9]
	global_store_dwordx4 v[12:13], v[8:11], off offset:-3072 sc1
	s_cbranch_scc1 .LBB0_495
